# v29 + streaming nt hint on the 16 x-row loads of the P0 rmsnorm
# baseline (speedup 1.0000x reference)
; __host__ __device__ __forceinline__ size_t blk(int r, int k, int K) { return (((size_t)((r >> 8) * (K >> 6) + (k >> 6))) << 14) + (size_t)(((r & 255) << 6) + (k & 63)); }
; __device__ __forceinline__ unsigned pk2(float lo, float hi) { f32x2 v = {lo, hi}; bf16x2_t b = __builtin_convertvector(v, bf16x2_t); return __builtin_bit_cast(unsigned, b); }
;     const f32x4* xr = (const f32x4*)xrow + lane; const f32x4* gr = (const f32x4*)g + lane;
;     f32x4 v[16]; float s = 0.f;
; #pragma unroll
;     for (int j = 0; j < 16; ++j) { v[j] = __builtin_nontemporal_load(xr + 64 * j); s += (v[j].x * v[j].x + v[j].y * v[j].y) + (v[j].z * v[j].z + v[j].w * v[j].w); }
;     const float rstd = 1.0f / sqrtf(wave_sum(s) * (1.0f / D) + RMS_EPS);
; #pragma unroll
;     for (int j = 0; j < 16; ++j) v[j] = v[j] * rstd * gr[64 * j];
;     if (MODE == 2) {
; #pragma unroll
;         for (int j = 0; j < 16; ++j) ((f32x4*)orow + lane)[64 * j] = v[j];
;     } else {
; #pragma unroll
;         for (int j = 0; j < 16; ++j) { u32x2 w; w.x = pk2(v[j].x, v[j].y); w.y = pk2(v[j].z, v[j].w); *(u32x2*)(hrow + blk(mrow, 4 * lane + 256 * j, D)) = w; }
.LBB0_53:
	v_add_co_u32_e64 v82, s[0:1], s6, v126
	v_add_co_u32_e32 v128, vcc, 0xffffd000, v126
	s_nop 0
	v_addc_co_u32_e64 v83, s[0:1], -1, v127, s[0:1]
	v_add_co_u32_e64 v84, s[0:1], s7, v126
	global_load_dwordx4 v[2:5], v[126:127], off offset:-3072 nt
	global_load_dwordx4 v[6:9], v[126:127], off offset:-2048 nt
	global_load_dwordx4 v[10:13], v[126:127], off offset:-1024 nt
	global_load_dwordx4 v[14:17], v[126:127], off nt
	global_load_dwordx4 v[18:21], v[100:101], off nt
	global_load_dwordx4 v[22:25], v[100:101], off offset:1024 nt
	global_load_dwordx4 v[26:29], v[100:101], off offset:2048 nt
	global_load_dwordx4 v[30:33], v[100:101], off offset:3072 nt
	global_load_dwordx4 v[34:37], v[102:103], off nt
	global_load_dwordx4 v[38:41], v[104:105], off nt
	global_load_dwordx4 v[42:45], v[106:107], off nt
	global_load_dwordx4 v[46:49], v[108:109], off nt
	global_load_dwordx4 v[50:53], v[110:111], off nt
	global_load_dwordx4 v[54:57], v[112:113], off nt
	global_load_dwordx4 v[58:61], v[114:115], off nt
	global_load_dwordx4 v[62:65], v[116:117], off nt
	global_load_dwordx4 v[66:69], v[118:119], off nt
	global_load_dwordx4 v[70:73], v[120:121], off nt
	global_load_dwordx4 v[74:77], v[122:123], off nt
	global_load_dwordx4 v[78:81], v[124:125], off nt
	v_addc_co_u32_e64 v85, s[0:1], -1, v127, s[0:1]
	global_load_dwordx4 v[170:173], v[82:83], off offset:-3072 nt
	global_load_dwordx4 v[174:177], v[82:83], off offset:-2048 nt
	global_load_dwordx4 v[180:183], v[82:83], off offset:-1024 nt
	global_load_dwordx4 v[184:187], v[82:83], off nt
	global_load_dwordx4 v[94:97], v[84:85], off offset:-3072 nt
	global_load_dwordx4 v[90:93], v[84:85], off offset:-2048 nt
	global_load_dwordx4 v[86:89], v[84:85], off offset:-1024 nt
	s_nop 0
	global_load_dwordx4 v[82:85], v[126:127], off offset:-4096 nt
	v_addc_co_u32_e32 v129, vcc, -1, v127, vcc
	global_load_dwordx4 v[188:191], v[128:129], off offset:-3072 nt
	global_load_dwordx4 v[196:199], v[128:129], off offset:-2048 nt
	global_load_dwordx4 v[200:203], v[128:129], off offset:-1024 nt
	global_load_dwordx4 v[204:207], v[128:129], off nt
	s_ashr_i32 s0, s13, 2
	s_andn2_b32 s0, s0, 63
	s_and_b32 s1, s3, 0x3fc0
	v_or_b32_e32 v128, s0, v160
	v_or_b32_e32 v98, s1, v1
	v_or_b32_e32 v130, 4, v128
	v_or_b32_e32 v132, 8, v128
	v_or_b32_e32 v134, 12, v128
	v_or_b32_e32 v136, 16, v128
	v_or_b32_e32 v138, 20, v128
	v_or_b32_e32 v140, 24, v128
	v_or_b32_e32 v142, 28, v128
	v_or_b32_e32 v144, 32, v128
	v_or_b32_e32 v146, 36, v128
	v_or_b32_e32 v148, 40, v128
	v_or_b32_e32 v150, 44, v128
	v_or_b32_e32 v152, 48, v128
	v_or_b32_e32 v154, 52, v128
	v_or_b32_e32 v156, 56, v128
	v_or_b32_e32 v208, 60, v128
	v_lshlrev_b32_e32 v98, 1, v98
	v_ashrrev_i32_e32 v129, 31, v128
	v_ashrrev_i32_e32 v131, 31, v130
	v_ashrrev_i32_e32 v133, 31, v132
	v_ashrrev_i32_e32 v135, 31, v134
	v_ashrrev_i32_e32 v137, 31, v136
	v_ashrrev_i32_e32 v139, 31, v138
	v_ashrrev_i32_e32 v141, 31, v140
	v_ashrrev_i32_e32 v143, 31, v142
	v_ashrrev_i32_e32 v145, 31, v144
	v_ashrrev_i32_e32 v147, 31, v146
	v_ashrrev_i32_e32 v149, 31, v148
	v_ashrrev_i32_e32 v151, 31, v150
	v_ashrrev_i32_e32 v153, 31, v152
	v_ashrrev_i32_e32 v155, 31, v154
	v_ashrrev_i32_e32 v157, 31, v156
	v_ashrrev_i32_e32 v209, 31, v208
	v_lshl_add_u64 v[158:159], s[66:67], 0, v[98:99]
	v_lshlrev_b64 v[128:129], 15, v[128:129]
	v_lshlrev_b64 v[130:131], 15, v[130:131]
	v_lshlrev_b64 v[132:133], 15, v[132:133]
	v_lshlrev_b64 v[134:135], 15, v[134:135]
	v_lshlrev_b64 v[136:137], 15, v[136:137]
	v_lshlrev_b64 v[138:139], 15, v[138:139]
	v_lshlrev_b64 v[140:141], 15, v[140:141]
	v_lshlrev_b64 v[142:143], 15, v[142:143]
	v_lshlrev_b64 v[144:145], 15, v[144:145]
	v_lshlrev_b64 v[146:147], 15, v[146:147]
	v_lshlrev_b64 v[148:149], 15, v[148:149]
	v_lshlrev_b64 v[150:151], 15, v[150:151]
	v_lshlrev_b64 v[152:153], 15, v[152:153]
	v_lshlrev_b64 v[154:155], 15, v[154:155]
	v_lshlrev_b64 v[156:157], 15, v[156:157]
	v_lshlrev_b64 v[208:209], 15, v[208:209]
	v_lshl_add_u64 v[128:129], v[158:159], 0, v[128:129]
	v_lshl_add_u64 v[130:131], v[158:159], 0, v[130:131]
	s_waitcnt vmcnt(29)
	v_mul_f32_e32 v98, v11, v11
	v_lshl_add_u64 v[132:133], v[158:159], 0, v[132:133]
	v_lshl_add_u64 v[134:135], v[158:159], 0, v[134:135]
	v_lshl_add_u64 v[136:137], v[158:159], 0, v[136:137]
	v_lshl_add_u64 v[138:139], v[158:159], 0, v[138:139]
	v_lshl_add_u64 v[140:141], v[158:159], 0, v[140:141]
	v_lshl_add_u64 v[142:143], v[158:159], 0, v[142:143]
	v_lshl_add_u64 v[144:145], v[158:159], 0, v[144:145]
	v_lshl_add_u64 v[146:147], v[158:159], 0, v[146:147]
	v_lshl_add_u64 v[148:149], v[158:159], 0, v[148:149]
	v_lshl_add_u64 v[150:151], v[158:159], 0, v[150:151]
	v_lshl_add_u64 v[152:153], v[158:159], 0, v[152:153]
	v_lshl_add_u64 v[154:155], v[158:159], 0, v[154:155]
	v_lshl_add_u64 v[156:157], v[158:159], 0, v[156:157]
	v_lshl_add_u64 v[158:159], v[158:159], 0, v[208:209]
	v_pk_mul_f32 v[208:209], v[8:9], v[8:9]
	v_pk_mul_f32 v[210:211], v[6:7], v[6:7]
	s_waitcnt vmcnt(28)
	v_mul_f32_e32 v219, v16, v16
	v_mul_f32_e32 v212, v13, v13
	s_waitcnt vmcnt(11)
	v_pk_mul_f32 v[214:215], v[172:173], v[172:173]
	v_pk_mul_f32 v[216:217], v[170:171], v[170:171]
	s_waitcnt vmcnt(10)
	v_mul_f32_e32 v218, v175, v175
	s_waitcnt vmcnt(8)
	v_pk_mul_f32 v[222:223], v[186:187], v[186:187]
	v_pk_mul_f32 v[224:225], v[184:185], v[184:185]
	s_waitcnt vmcnt(5)
	v_pk_mul_f32 v[230:231], v[88:89], v[88:89]
	v_pk_mul_f32 v[232:233], v[86:87], v[86:87]
	v_pk_fma_f32 v[242:243], v[10:11], v[10:11], v[98:99] op_sel_hi:[1,1,0]
	v_mul_f32_e32 v221, v17, v17
	v_mul_f32_e32 v227, v182, v182
	v_mul_f32_e32 v229, v183, v183
	v_mul_f32_e32 v220, v177, v177
	v_mul_f32_e32 v226, v95, v95
	v_mul_f32_e32 v228, v97, v97
	v_pk_mov_b32 v[234:235], v[210:211], v[208:209] op_sel:[1,0]
	v_mov_b32_e32 v211, v209
	s_waitcnt vmcnt(3)
; __device__ __forceinline__ float wave_sum(float v) {
; #pragma unroll
;     for (int o = 1; o < 64; o <<= 1) v += __shfl_xor(v, o);
;     return v;
; }
;     ...
;     for (int j = 0; j < 16; ++j) { v[j] = __builtin_nontemporal_load(xr + 64 * j); s += (v[j].x * v[j].x + v[j].y * v[j].y) + (v[j].z * v[j].z + v[j].w * v[j].w); }
;     const float rstd = 1.0f / sqrtf(wave_sum(s) * (1.0f / D) + RMS_EPS);
	v_pk_mul_f32 v[208:209], v[190:191], v[190:191]
	v_pk_mul_f32 v[236:237], v[188:189], v[188:189]
	s_waitcnt vmcnt(2)
	v_pk_mul_f32 v[238:239], v[198:199], v[198:199]
	v_pk_mov_b32 v[240:241], v[216:217], v[214:215] op_sel:[1,0]
	v_mov_b32_e32 v217, v215
	v_pk_mov_b32 v[214:215], v[224:225], v[222:223] op_sel:[1,0]
	v_mov_b32_e32 v225, v223
	v_pk_mov_b32 v[222:223], v[232:233], v[230:231] op_sel:[1,0]
	v_mov_b32_e32 v233, v231
	v_pk_mul_f32 v[230:231], v[196:197], v[196:197]
	v_pk_fma_f32 v[212:213], v[12:13], v[12:13], v[212:213] op_sel_hi:[1,1,0]
	v_mov_b32_e32 v243, v219
	v_pk_fma_f32 v[218:219], v[174:175], v[174:175], v[218:219] op_sel_hi:[1,1,0]
	v_mul_f32_e32 v244, v92, v92
	v_mul_f32_e32 v245, v93, v93
	v_pk_add_f32 v[210:211], v[234:235], v[210:211]
	v_pk_mov_b32 v[234:235], v[236:237], v[208:209] op_sel:[1,0]
	v_mov_b32_e32 v237, v209
	v_pk_mov_b32 v[208:209], v[230:231], v[238:239] op_sel:[1,0]
	v_mov_b32_e32 v231, v239
	v_mov_b32_e32 v213, v221
	v_mov_b32_e32 v219, v227
	v_pk_fma_f32 v[220:221], v[176:177], v[176:177], v[220:221] op_sel_hi:[1,1,0]
	v_pk_add_f32 v[214:215], v[214:215], v[224:225]
	v_pk_fma_f32 v[224:225], v[94:95], v[94:95], v[226:227] op_sel_hi:[1,1,0]
	v_pk_fma_f32 v[226:227], v[96:97], v[96:97], v[228:229] op_sel_hi:[1,1,0]
	v_mov_b32_e32 v221, v229
	s_waitcnt vmcnt(1)
	v_mul_f32_e32 v98, v201, v201
	v_mov_b32_e32 v225, v244
	v_mov_b32_e32 v227, v245
	v_mul_f32_e32 v228, v203, v203
	v_pk_add_f32 v[222:223], v[222:223], v[232:233]
	v_pk_add_f32 v[232:233], v[234:235], v[236:237]
	v_pk_add_f32 v[208:209], v[208:209], v[230:231]
	s_waitcnt vmcnt(0)
	v_mul_f32_e32 v253, v204, v204
	v_mul_f32_e32 v254, v205, v205
	v_mul_f32_e32 v194, v206, v206
	v_mul_f32_e32 v178, v207, v207
	v_pk_fma_f32 v[244:245], v[200:201], v[200:201], v[98:99] op_sel_hi:[1,1,0]
	v_pk_fma_f32 v[228:229], v[202:203], v[202:203], v[228:229] op_sel_hi:[1,1,0]
	v_pk_add_f32 v[218:219], v[218:219], v[220:221]
	v_pk_add_f32 v[220:221], v[224:225], v[226:227]
	v_pk_add_f32 v[226:227], v[232:233], v[232:233] op_sel:[0,1] op_sel_hi:[1,0]
	v_pk_add_f32 v[208:209], v[208:209], v[208:209] op_sel:[0,1] op_sel_hi:[1,0]
	v_mov_b32_e32 v245, v194
	v_mov_b32_e32 v229, v178
	v_mov_b32_e32 v227, v253
	v_mov_b32_e32 v209, v254
	v_pk_add_f32 v[228:229], v[244:245], v[228:229]
	v_pk_add_f32 v[208:209], v[226:227], v[208:209]
	v_pk_add_f32 v[216:217], v[240:241], v[216:217]
	v_pk_add_f32 v[208:209], v[208:209], v[228:229]
	v_mul_f32_e32 v249, v180, v180
	v_mul_f32_e32 v250, v181, v181
	v_pk_add_f32 v[216:217], v[216:217], v[216:217] op_sel:[0,1] op_sel_hi:[1,0]
	v_pk_add_f32 v[208:209], v[208:209], v[208:209] op_sel:[0,1] op_sel_hi:[1,0]
	v_mov_b32_e32 v217, v250
	v_mov_b32_e32 v209, v249
	v_pk_add_f32 v[208:209], v[208:209], v[216:217]
	v_mul_f32_e32 v251, v90, v90
	v_pk_add_f32 v[208:209], v[208:209], v[218:219]
	v_mul_f32_e32 v252, v91, v91
	v_pk_add_f32 v[214:215], v[214:215], v[214:215] op_sel:[0,1] op_sel_hi:[1,0]
	v_pk_add_f32 v[208:209], v[208:209], v[208:209] op_sel:[0,1] op_sel_hi:[1,0]
	v_mov_b32_e32 v215, v252
	v_mov_b32_e32 v209, v251
	v_pk_add_f32 v[208:209], v[208:209], v[214:215]
	v_mul_f32_e32 v238, v83, v83
	v_mul_f32_e32 v240, v85, v85
	v_pk_add_f32 v[208:209], v[208:209], v[220:221]
	v_mul_f32_e32 v169, v2, v2
	v_mul_f32_e32 v179, v3, v3
	v_mul_f32_e32 v195, v4, v4
	v_mul_f32_e32 v246, v5, v5
	v_pk_fma_f32 v[238:239], v[82:83], v[82:83], v[238:239] op_sel_hi:[1,1,0]
	v_pk_fma_f32 v[240:241], v[84:85], v[84:85], v[240:241] op_sel_hi:[1,1,0]
	v_pk_add_f32 v[222:223], v[222:223], v[222:223] op_sel:[0,1] op_sel_hi:[1,0]
	v_pk_add_f32 v[208:209], v[208:209], v[208:209] op_sel:[0,1] op_sel_hi:[1,0]
	v_mov_b32_e32 v239, v195
	v_mov_b32_e32 v241, v246
	v_mov_b32_e32 v223, v179
	v_mov_b32_e32 v209, v169
	v_pk_add_f32 v[224:225], v[238:239], v[240:241]
	v_pk_add_f32 v[208:209], v[208:209], v[222:223]
	v_mul_f32_e32 v247, v14, v14
	v_pk_add_f32 v[208:209], v[208:209], v[224:225]
	v_mul_f32_e32 v248, v15, v15
	v_pk_add_f32 v[210:211], v[210:211], v[210:211] op_sel:[0,1] op_sel_hi:[1,0]
	v_pk_add_f32 v[208:209], v[208:209], v[208:209] op_sel:[0,1] op_sel_hi:[1,0]
	v_mov_b32_e32 v211, v248
	v_mov_b32_e32 v209, v247
	v_pk_add_f32 v[212:213], v[242:243], v[212:213]
	v_pk_add_f32 v[208:209], v[208:209], v[210:211]
	s_add_i32 s13, s13, s94
	v_pk_add_f32 v[208:209], v[208:209], v[212:213]
	s_add_i32 s3, s3, s72
	v_add_f32_e32 v98, v208, v209
	ds_bpermute_b32 v169, v161, v98
	v_lshl_add_u64 v[126:127], v[126:127], 0, s[10:11]
	s_cmpk_lt_i32 s13, 0x2000
	s_waitcnt lgkmcnt(0)
	v_add_f32_e32 v98, v98, v169
	ds_bpermute_b32 v169, v162, v98
	s_waitcnt lgkmcnt(0)
	v_add_f32_e32 v98, v98, v169
	ds_bpermute_b32 v169, v163, v98
	s_waitcnt lgkmcnt(0)
	v_add_f32_e32 v98, v98, v169
	ds_bpermute_b32 v169, v164, v98
	s_waitcnt lgkmcnt(0)
	v_add_f32_e32 v98, v98, v169
	ds_bpermute_b32 v169, v165, v98
	s_waitcnt lgkmcnt(0)
	v_add_f32_e32 v98, v98, v169
	ds_bpermute_b32 v169, v166, v98
	s_waitcnt lgkmcnt(0)
; __host__ __device__ __forceinline__ size_t blk(int r, int k, int K) { return (((size_t)((r >> 8) * (K >> 6) + (k >> 6))) << 14) + (size_t)(((r & 255) << 6) + (k & 63)); }
; __device__ __forceinline__ unsigned pk2(float lo, float hi) { f32x2 v = {lo, hi}; bf16x2_t b = __builtin_convertvector(v, bf16x2_t); return __builtin_bit_cast(unsigned, b); }
;     ...
;     const float rstd = 1.0f / sqrtf(wave_sum(s) * (1.0f / D) + RMS_EPS);
; #pragma unroll
;     for (int j = 0; j < 16; ++j) v[j] = v[j] * rstd * gr[64 * j];
;     if (MODE == 2) {
; #pragma unroll
;         for (int j = 0; j < 16; ++j) ((f32x4*)orow + lane)[64 * j] = v[j];
;     } else {
; #pragma unroll
;         for (int j = 0; j < 16; ++j) { u32x2 w; w.x = pk2(v[j].x, v[j].y); w.y = pk2(v[j].z, v[j].w); *(u32x2*)(hrow + blk(mrow, 4 * lane + 256 * j, D)) = w; }
	v_add_f32_e32 v98, v98, v169
	v_fmamk_f32 v98, v98, 0x39800000, v167
	v_mul_f32_e32 v169, 0x4f800000, v98
	v_cmp_gt_f32_e32 vcc, s12, v98
	s_nop 1
	v_cndmask_b32_e32 v98, v98, v169, vcc
	v_sqrt_f32_e32 v169, v98
	s_nop 0
	v_add_u32_e32 v178, -1, v169
	v_add_u32_e32 v179, 1, v169
	v_fma_f32 v194, -v178, v169, v98
	v_fma_f32 v195, -v179, v169, v98
	v_cmp_ge_f32_e64 s[0:1], 0, v194
	s_nop 1
	v_cndmask_b32_e64 v169, v169, v178, s[0:1]
	v_cmp_lt_f32_e64 s[0:1], 0, v195
	s_nop 1
	v_cndmask_b32_e64 v169, v169, v179, s[0:1]
	v_mul_f32_e32 v178, 0x37800000, v169
	v_cndmask_b32_e32 v169, v169, v178, vcc
	v_cmp_class_f32_e32 vcc, v98, v168
	s_nop 1
	v_cndmask_b32_e32 v98, v169, v98, vcc
	v_div_scale_f32 v169, s[0:1], v98, v98, 1.0
	v_rcp_f32_e32 v179, v169
	v_div_scale_f32 v178, vcc, 1.0, v98, 1.0
	v_fma_f32 v194, -v169, v179, 1.0
	v_fmac_f32_e32 v179, v194, v179
	v_mul_f32_e32 v194, v178, v179
	v_fma_f32 v195, -v169, v194, v178
	v_fmac_f32_e32 v194, v195, v179
	v_fma_f32 v169, -v169, v194, v178
	v_div_fmas_f32 v169, v169, v179, v194
	v_div_fixup_f32 v98, v169, v98, 1.0
	v_pk_mul_f32 v[188:189], v[188:189], v[98:99] op_sel_hi:[1,0]
	v_pk_mul_f32 v[190:191], v[190:191], v[98:99] op_sel_hi:[1,0]
	v_pk_mul_f32 v[196:197], v[196:197], v[98:99] op_sel_hi:[1,0]
	v_pk_mul_f32 v[198:199], v[198:199], v[98:99] op_sel_hi:[1,0]
	v_pk_mul_f32 v[200:201], v[200:201], v[98:99] op_sel_hi:[1,0]
	v_pk_mul_f32 v[202:203], v[202:203], v[98:99] op_sel_hi:[1,0]
	v_pk_mul_f32 v[204:205], v[204:205], v[98:99] op_sel_hi:[1,0]
	v_pk_mul_f32 v[206:207], v[206:207], v[98:99] op_sel_hi:[1,0]
	v_pk_mul_f32 v[170:171], v[170:171], v[98:99] op_sel_hi:[1,0]
	v_pk_mul_f32 v[172:173], v[172:173], v[98:99] op_sel_hi:[1,0]
	v_pk_mul_f32 v[174:175], v[174:175], v[98:99] op_sel_hi:[1,0]
	v_pk_mul_f32 v[176:177], v[176:177], v[98:99] op_sel_hi:[1,0]
	v_pk_mul_f32 v[180:181], v[180:181], v[98:99] op_sel_hi:[1,0]
	v_pk_mul_f32 v[182:183], v[182:183], v[98:99] op_sel_hi:[1,0]
	v_pk_mul_f32 v[184:185], v[184:185], v[98:99] op_sel_hi:[1,0]
	v_pk_mul_f32 v[186:187], v[186:187], v[98:99] op_sel_hi:[1,0]
	v_pk_mul_f32 v[94:95], v[94:95], v[98:99] op_sel_hi:[1,0]
	v_pk_mul_f32 v[96:97], v[96:97], v[98:99] op_sel_hi:[1,0]
	v_pk_mul_f32 v[90:91], v[90:91], v[98:99] op_sel_hi:[1,0]
	v_pk_mul_f32 v[92:93], v[92:93], v[98:99] op_sel_hi:[1,0]
	v_pk_mul_f32 v[86:87], v[86:87], v[98:99] op_sel_hi:[1,0]
	v_pk_mul_f32 v[88:89], v[88:89], v[98:99] op_sel_hi:[1,0]
	v_pk_mul_f32 v[82:83], v[82:83], v[98:99] op_sel_hi:[1,0]
	v_pk_mul_f32 v[84:85], v[84:85], v[98:99] op_sel_hi:[1,0]
	v_pk_mul_f32 v[2:3], v[2:3], v[98:99] op_sel_hi:[1,0]
	v_pk_mul_f32 v[4:5], v[4:5], v[98:99] op_sel_hi:[1,0]
	v_pk_mul_f32 v[6:7], v[6:7], v[98:99] op_sel_hi:[1,0]
	v_pk_mul_f32 v[8:9], v[8:9], v[98:99] op_sel_hi:[1,0]
	v_pk_mul_f32 v[10:11], v[10:11], v[98:99] op_sel_hi:[1,0]
	v_pk_mul_f32 v[12:13], v[12:13], v[98:99] op_sel_hi:[1,0]
	v_pk_mul_f32 v[14:15], v[14:15], v[98:99] op_sel_hi:[1,0]
	v_pk_mul_f32 v[16:17], v[16:17], v[98:99] op_sel_hi:[1,0]
	v_pk_mul_f32 v[20:21], v[20:21], v[190:191]
	v_pk_mul_f32 v[18:19], v[18:19], v[188:189]
	v_pk_mul_f32 v[24:25], v[24:25], v[198:199]
	v_pk_mul_f32 v[22:23], v[22:23], v[196:197]
	v_pk_mul_f32 v[28:29], v[28:29], v[202:203]
	v_pk_mul_f32 v[26:27], v[26:27], v[200:201]
	v_pk_mul_f32 v[32:33], v[32:33], v[206:207]
	v_pk_mul_f32 v[30:31], v[30:31], v[204:205]
	v_pk_mul_f32 v[36:37], v[36:37], v[172:173]
	v_pk_mul_f32 v[34:35], v[34:35], v[170:171]
	v_pk_mul_f32 v[40:41], v[40:41], v[176:177]
	v_pk_mul_f32 v[38:39], v[38:39], v[174:175]
	v_pk_mul_f32 v[44:45], v[44:45], v[182:183]
	v_pk_mul_f32 v[42:43], v[42:43], v[180:181]
	v_pk_mul_f32 v[48:49], v[48:49], v[186:187]
	v_pk_mul_f32 v[46:47], v[46:47], v[184:185]
	v_pk_mul_f32 v[52:53], v[52:53], v[96:97]
	v_pk_mul_f32 v[50:51], v[50:51], v[94:95]
	v_pk_mul_f32 v[56:57], v[92:93], v[56:57]
	v_pk_mul_f32 v[54:55], v[90:91], v[54:55]
	v_pk_mul_f32 v[60:61], v[88:89], v[60:61]
	v_pk_mul_f32 v[58:59], v[86:87], v[58:59]
	v_pk_mul_f32 v[64:65], v[84:85], v[64:65]
	v_pk_mul_f32 v[62:63], v[82:83], v[62:63]
	v_pk_mul_f32 v[4:5], v[4:5], v[68:69]
	v_pk_mul_f32 v[2:3], v[2:3], v[66:67]
	v_pk_mul_f32 v[8:9], v[8:9], v[72:73]
	v_pk_mul_f32 v[6:7], v[6:7], v[70:71]
	v_pk_mul_f32 v[12:13], v[12:13], v[76:77]
	v_pk_mul_f32 v[10:11], v[10:11], v[74:75]
	v_pk_mul_f32 v[16:17], v[16:17], v[80:81]
	v_pk_mul_f32 v[14:15], v[14:15], v[78:79]
	v_cvt_pk_bf16_f32 v18, v18, v19
	v_cvt_pk_bf16_f32 v19, v20, v21
	v_cvt_pk_bf16_f32 v20, v22, v23
	v_cvt_pk_bf16_f32 v21, v24, v25
	v_cvt_pk_bf16_f32 v22, v26, v27
	v_cvt_pk_bf16_f32 v23, v28, v29
	v_cvt_pk_bf16_f32 v24, v30, v31
	v_cvt_pk_bf16_f32 v25, v32, v33
	v_cvt_pk_bf16_f32 v26, v34, v35
	v_cvt_pk_bf16_f32 v27, v36, v37
	v_cvt_pk_bf16_f32 v28, v38, v39
	v_cvt_pk_bf16_f32 v29, v40, v41
	v_cvt_pk_bf16_f32 v30, v42, v43
	v_cvt_pk_bf16_f32 v31, v44, v45
	v_cvt_pk_bf16_f32 v32, v46, v47
	v_cvt_pk_bf16_f32 v33, v48, v49
	v_cvt_pk_bf16_f32 v34, v50, v51
	v_cvt_pk_bf16_f32 v35, v52, v53
	v_cvt_pk_bf16_f32 v36, v54, v55
	v_cvt_pk_bf16_f32 v37, v56, v57
	v_cvt_pk_bf16_f32 v38, v58, v59
	v_cvt_pk_bf16_f32 v39, v60, v61
	v_cvt_pk_bf16_f32 v40, v62, v63
	v_cvt_pk_bf16_f32 v41, v64, v65
	v_cvt_pk_bf16_f32 v2, v2, v3
	v_cvt_pk_bf16_f32 v3, v4, v5
	v_cvt_pk_bf16_f32 v4, v6, v7
	v_cvt_pk_bf16_f32 v5, v8, v9
	v_cvt_pk_bf16_f32 v6, v10, v11
	v_cvt_pk_bf16_f32 v7, v12, v13
	v_cvt_pk_bf16_f32 v8, v14, v15
	v_cvt_pk_bf16_f32 v9, v16, v17
	global_store_dwordx2 v[128:129], v[18:19], off nt
	global_store_dwordx2 v[130:131], v[20:21], off nt
	global_store_dwordx2 v[132:133], v[22:23], off nt
	global_store_dwordx2 v[134:135], v[24:25], off nt
	global_store_dwordx2 v[136:137], v[26:27], off nt
	global_store_dwordx2 v[138:139], v[28:29], off nt
	global_store_dwordx2 v[140:141], v[30:31], off nt
	global_store_dwordx2 v[142:143], v[32:33], off nt
	global_store_dwordx2 v[144:145], v[34:35], off nt
	global_store_dwordx2 v[146:147], v[36:37], off nt
	global_store_dwordx2 v[148:149], v[38:39], off nt
	global_store_dwordx2 v[150:151], v[40:41], off nt
	global_store_dwordx2 v[152:153], v[2:3], off nt
	global_store_dwordx2 v[154:155], v[4:5], off nt
	global_store_dwordx2 v[156:157], v[6:7], off nt
	global_store_dwordx2 v[158:159], v[8:9], off nt
	s_cbranch_scc1 .LBB0_53
	v_readlane_b32 s95, v255, 25
	v_lshlrev_b32_e32 v252, 2, v0
	v_lshlrev_b32_e32 v251, 3, v0
